# grid barrier: every waiter polls the top-level arrival counter against (generation+1)*groups, so the last XCD's arrival releases everyone directly; the generation words are no longer written
# baseline (speedup 1.0000x reference)
.LBB0_31:
	s_or_b64 exec, exec, s[2:3]
	v_cvt_f32_u32_e32 v5, v3
	s_waitcnt vmcnt(0)
	v_readfirstlane_b32 s2, v4
	v_sub_u32_e32 v4, 0, v3
	v_rcp_iflag_f32_e32 v5, v5
	v_add_u32_e32 v6, s2, v0
	v_mul_f32_e32 v5, 0x4f7ffffe, v5
	v_cvt_u32_f32_e32 v5, v5
	v_mul_lo_u32 v0, v4, v5
	v_mul_hi_u32 v0, v5, v0
	v_add_u32_e32 v0, v5, v0
	v_mul_hi_u32 v0, v6, v0
	v_mul_lo_u32 v4, v0, v3
	v_sub_u32_e32 v4, v6, v4
	v_add_u32_e32 v5, 1, v0
	v_cmp_ge_u32_e32 vcc, v4, v3
	s_nop 1
	v_cndmask_b32_e32 v0, v0, v5, vcc
	v_sub_u32_e32 v5, v4, v3
	v_cndmask_b32_e32 v4, v4, v5, vcc
	v_add_u32_e32 v5, 1, v0
	v_cmp_ge_u32_e32 vcc, v4, v3
	v_add_u32_e32 v4, 1, v6
	s_nop 0
	v_cndmask_b32_e32 v0, v0, v5, vcc
	v_mul_lo_u32 v5, v3, v0
	v_add_u32_e32 v3, v5, v3
	v_cmp_ne_u32_e32 vcc, v4, v3
	s_and_saveexec_b64 s[2:3], vcc
	s_xor_b64 s[2:3], exec, s[2:3]
	s_cbranch_execz .LBB0_45
	v_readlane_b32 s8, v254, 49
	v_readlane_b32 s9, v254, 50
	s_waitcnt lgkmcnt(0)
	v_mad_u32_u24 v7, v0, v2, v2
	s_nop 3
	global_load_dword v2, v1, s[8:9] sc1
	s_waitcnt vmcnt(0)
	v_cmp_lt_u32_e32 vcc, v2, v7
	s_and_saveexec_b64 s[8:9], vcc
	s_cbranch_execz .LBB0_44
	s_mov_b32 s24, 1
	s_mov_b64 s[10:11], 0
	s_branch .LBB0_35

.LBB0_39:
	v_readlane_b32 s14, v254, 49
	v_readlane_b32 s15, v254, 50
	s_add_i32 s24, s24, 1
	s_mov_b64 s[18:19], -1
	s_nop 2
	global_load_dword v2, v1, s[14:15] sc1
	s_waitcnt vmcnt(0)
	v_cmp_ge_u32_e32 vcc, v2, v7
	s_orn2_b64 s[14:15], vcc, exec
	s_branch .LBB0_34

.LBB0_48:
	s_or_b64 exec, exec, s[8:9]
	v_cvt_f32_u32_e32 v4, v2
	s_waitcnt vmcnt(0)
	v_readfirstlane_b32 s2, v3
	s_mov_b64 s[8:9], 0
	v_rcp_iflag_f32_e32 v4, v4
	v_add_u32_e32 v0, s2, v0
	v_add_u32_e32 v5, 1, v0
	v_readlane_b32 s2, v254, 51
	v_mul_f32_e32 v3, 0x4f7ffffe, v4
	v_cvt_u32_f32_e32 v3, v3
	v_sub_u32_e32 v4, 0, v2
	v_readlane_b32 s3, v254, 52
	v_mul_lo_u32 v4, v4, v3
	v_mul_hi_u32 v4, v3, v4
	v_add_u32_e32 v3, v3, v4
	v_mul_hi_u32 v3, v0, v3
	v_mul_lo_u32 v4, v3, v2
	v_sub_u32_e32 v0, v0, v4
	v_add_u32_e32 v6, 1, v3
	v_cmp_ge_u32_e32 vcc, v0, v2
	v_sub_u32_e32 v4, v0, v2
	s_nop 0
	v_cndmask_b32_e32 v3, v3, v6, vcc
	v_cndmask_b32_e32 v0, v0, v4, vcc
	v_add_u32_e32 v4, 1, v3
	v_cmp_ge_u32_e32 vcc, v0, v2
	s_nop 1
	v_cndmask_b32_e32 v0, v3, v4, vcc
	v_mul_lo_u32 v3, v2, v0
	v_add_u32_e32 v2, v3, v2
	v_cmp_ne_u32_e32 vcc, v5, v2
	v_mov_b32_e32 v7, v2
	v_mov_b64_e32 v[2:3], s[2:3]
	s_and_saveexec_b64 s[2:3], vcc
	s_cbranch_execz .LBB0_60
	v_readlane_b32 s8, v254, 49
	v_readlane_b32 s9, v254, 50
	s_mov_b64 s[10:11], 0
	s_nop 3
	global_load_dword v2, v1, s[8:9] sc1
	s_waitcnt vmcnt(0)
	v_cmp_lt_u32_e32 vcc, v2, v7
	s_and_saveexec_b64 s[8:9], vcc
	s_cbranch_execz .LBB0_59
	s_mov_b32 s24, 1
	s_branch .LBB0_52

.LBB0_62:
	s_or_b64 exec, exec, s[2:3]
	s_mov_b64 s[2:3], exec
	v_mbcnt_lo_u32_b32 v0, s2, 0
	v_mbcnt_hi_u32_b32 v0, s3, v0
	v_cmp_eq_u32_e32 vcc, 0, v0
	s_waitcnt vmcnt(0)
	buffer_inv sc1
	s_and_saveexec_b64 s[8:9], vcc
	s_cbranch_execz .LBB0_64
	s_bcnt1_i32_b64 s2, s[2:3]
	v_mov_b32_e32 v0, s2
	v_readlane_b32 s2, v254, 47
	v_readlane_b32 s3, v254, 48
	s_nop 4
	s_nop 0

.LBB0_351:
	s_or_b64 exec, exec, s[10:11]
	v_cvt_f32_u32_e32 v5, v3
	s_waitcnt vmcnt(0)
	v_readfirstlane_b32 s10, v4
	v_sub_u32_e32 v4, 0, v3
	v_rcp_iflag_f32_e32 v5, v5
	v_add_u32_e32 v6, s10, v0
	v_mul_f32_e32 v5, 0x4f7ffffe, v5
	v_cvt_u32_f32_e32 v5, v5
	v_mul_lo_u32 v0, v4, v5
	v_mul_hi_u32 v0, v5, v0
	v_add_u32_e32 v0, v5, v0
	v_mul_hi_u32 v0, v6, v0
	v_mul_lo_u32 v4, v0, v3
	v_sub_u32_e32 v4, v6, v4
	v_add_u32_e32 v5, 1, v0
	v_cmp_ge_u32_e32 vcc, v4, v3
	s_nop 1
	v_cndmask_b32_e32 v0, v0, v5, vcc
	v_sub_u32_e32 v5, v4, v3
	v_cndmask_b32_e32 v4, v4, v5, vcc
	v_add_u32_e32 v5, 1, v0
	v_cmp_ge_u32_e32 vcc, v4, v3
	v_add_u32_e32 v4, 1, v6
	s_nop 0
	v_cndmask_b32_e32 v0, v0, v5, vcc
	v_mul_lo_u32 v5, v3, v0
	v_add_u32_e32 v3, v5, v3
	v_cmp_ne_u32_e32 vcc, v4, v3
	s_and_saveexec_b64 s[10:11], vcc
	s_xor_b64 s[10:11], exec, s[10:11]
	s_cbranch_execz .LBB0_365
	v_readlane_b32 s14, v254, 49
	v_readlane_b32 s15, v254, 50
	s_waitcnt lgkmcnt(0)
	v_mad_u32_u24 v7, v0, v2, v2
	s_nop 3
	global_load_dword v2, v1, s[14:15] sc1
	s_waitcnt vmcnt(0)
	v_cmp_lt_u32_e32 vcc, v2, v7
	s_and_saveexec_b64 s[14:15], vcc
	s_cbranch_execz .LBB0_364
	s_mov_b32 s60, 1
	s_mov_b64 s[18:19], 0
	s_branch .LBB0_355

.LBB0_359:
	v_readlane_b32 s34, v254, 49
	v_readlane_b32 s35, v254, 50
	s_add_i32 s60, s60, 1
	s_mov_b64 s[38:39], -1
	s_nop 2
	global_load_dword v2, v1, s[34:35] sc1
	s_waitcnt vmcnt(0)
	v_cmp_ge_u32_e32 vcc, v2, v7
	s_orn2_b64 s[34:35], vcc, exec
	s_branch .LBB0_354

.LBB0_368:
	s_or_b64 exec, exec, s[14:15]
	s_waitcnt vmcnt(0)
	v_readfirstlane_b32 s10, v3
	v_sub_u32_e32 v4, 0, v2
	s_mov_b64 s[14:15], 0
	v_add_u32_e32 v3, s10, v0
	v_cvt_f32_u32_e32 v0, v2
	v_readlane_b32 s10, v254, 51
	v_readlane_b32 s11, v254, 52
	v_rcp_iflag_f32_e32 v0, v0
	s_nop 0
	v_mul_f32_e32 v0, 0x4f7ffffe, v0
	v_cvt_u32_f32_e32 v0, v0
	v_mul_lo_u32 v4, v4, v0
	v_mul_hi_u32 v4, v0, v4
	v_add_u32_e32 v0, v0, v4
	v_mul_hi_u32 v0, v3, v0
	v_mul_lo_u32 v4, v0, v2
	v_sub_u32_e32 v4, v3, v4
	v_cmp_ge_u32_e32 vcc, v4, v2
	v_add_u32_e32 v5, 1, v0
	v_add_u32_e32 v3, 1, v3
	v_cndmask_b32_e32 v0, v0, v5, vcc
	v_sub_u32_e32 v5, v4, v2
	v_cndmask_b32_e32 v4, v4, v5, vcc
	v_cmp_ge_u32_e32 vcc, v4, v2
	v_add_u32_e32 v4, 1, v0
	s_nop 0
	v_cndmask_b32_e32 v0, v0, v4, vcc
	v_mul_lo_u32 v4, v2, v0
	v_add_u32_e32 v2, v4, v2
	v_cmp_ne_u32_e32 vcc, v3, v2
	v_mov_b32_e32 v7, v2
	v_mov_b64_e32 v[2:3], s[10:11]
	s_and_saveexec_b64 s[10:11], vcc
	s_cbranch_execz .LBB0_380
	v_readlane_b32 s14, v254, 49
	v_readlane_b32 s15, v254, 50
	s_mov_b64 s[18:19], 0
	s_nop 3
	global_load_dword v2, v1, s[14:15] sc1
	s_waitcnt vmcnt(0)
	v_cmp_lt_u32_e32 vcc, v2, v7
	s_and_saveexec_b64 s[14:15], vcc
	s_cbranch_execz .LBB0_379
	s_mov_b32 s60, 1
	s_branch .LBB0_372

.LBB0_382:
	s_or_b64 exec, exec, s[10:11]
	s_mov_b64 s[10:11], exec
	v_mbcnt_lo_u32_b32 v0, s10, 0
	v_mbcnt_hi_u32_b32 v0, s11, v0
	v_cmp_eq_u32_e32 vcc, 0, v0
	s_waitcnt vmcnt(0)
	buffer_inv sc1
	s_and_saveexec_b64 s[14:15], vcc
	s_cbranch_execz .LBB0_384
	s_bcnt1_i32_b64 s10, s[10:11]
	v_mov_b32_e32 v0, s10
	v_readlane_b32 s10, v254, 47
	v_readlane_b32 s11, v254, 48
	s_nop 4
	s_nop 0
